# SwiGLU epilogue stores: rows 2..8 take the address as first-row address + constant (one v_lshl_add_u64) instead of v_add_u32 + v_mad_i64_i32 + v_lshl_add_u64 each
# baseline (speedup 1.0000x reference)
.LBB0_708:
	s_mov_b32 s99, 0
	v_lshl_add_u32 v154, s40, 10, v150
	ds_read2_b32 v[156:157], v154 offset1:16
	v_pk_mul_f32 v[120:121], v[124:125], v[120:121]
	v_pk_mul_f32 v[122:123], v[126:127], v[122:123]
	v_lshl_or_b32 v158, s41, 7, v149
	v_pk_mul_f32 v[114:115], v[118:119], v[114:115]
	s_waitcnt lgkmcnt(0)
	v_mul_f32_e32 v160, 0xbfb8aa3b, v156
	v_pk_mul_f32 v[164:165], v[124:125], v[160:161] op_sel_hi:[1,0]
	v_pk_mul_f32 v[162:163], v[126:127], v[160:161] op_sel_hi:[1,0]
	v_exp_f32_e32 v164, v164
	v_exp_f32_e32 v165, v165
	v_exp_f32_e32 v162, v162
	v_exp_f32_e32 v163, v163
	v_mul_f32_e32 v156, v156, v156
	v_rcp_f32_e32 v232, v156
	s_nop 0
	v_pk_fma_f32 v[164:165], v[164:165], v[232:233], v[232:233] op_sel_hi:[1,0,0]
	v_ashrrev_i32_e32 v159, 31, v158
	v_pk_fma_f32 v[162:163], v[162:163], v[232:233], v[232:233] op_sel_hi:[1,0,0]
	v_rcp_f32_e32 v164, v164
	v_rcp_f32_e32 v165, v165
	v_rcp_f32_e32 v162, v162
	v_rcp_f32_e32 v163, v163
	v_pk_mul_f32 v[112:113], v[116:117], v[112:113]
	v_pk_mul_f32 v[120:121], v[120:121], v[164:165]
	v_pk_mul_f32 v[124:125], v[118:119], v[160:161] op_sel_hi:[1,0]
	v_pk_mul_f32 v[122:123], v[122:123], v[162:163]
	v_pk_mul_f32 v[126:127], v[116:117], v[160:161] op_sel_hi:[1,0]
	v_exp_f32_e32 v124, v124
	v_exp_f32_e32 v125, v125
	v_exp_f32_e32 v126, v126
	v_exp_f32_e32 v127, v127
	v_cvt_pk_bf16_f32 v120, v120, v121
	v_cvt_pk_bf16_f32 v121, v122, v123
	v_pk_fma_f32 v[122:123], v[124:125], v[232:233], v[232:233] op_sel_hi:[1,0,0]
	v_pk_fma_f32 v[124:125], v[126:127], v[232:233], v[232:233] op_sel_hi:[1,0,0]
	v_rcp_f32_e32 v122, v122
	v_rcp_f32_e32 v123, v123
	v_rcp_f32_e32 v124, v124
	v_rcp_f32_e32 v125, v125
	s_lshl_b32 s11, s18, 8
	v_pk_mul_f32 v[114:115], v[114:115], v[122:123]
	v_pk_mul_f32 v[116:117], v[124:125], 1.0 op_sel_hi:[1,0]
	v_mul_f32_e32 v124, 0xbfb8aa3b, v157
	v_cvt_pk_bf16_f32 v123, v114, v115
	v_lshlrev_b64 v[114:115], 1, v[158:159]
	v_pk_mul_f32 v[126:127], v[110:111], v[124:125] op_sel_hi:[1,0]
	v_pk_mul_f32 v[158:159], v[108:109], v[124:125] op_sel_hi:[1,0]
	v_pk_mul_f32 v[112:113], v[112:113], v[116:117]
	v_exp_f32_e32 v158, v158
	v_exp_f32_e32 v126, v126
	v_exp_f32_e32 v127, v127
	v_exp_f32_e32 v159, v159
	v_cvt_pk_bf16_f32 v122, v112, v113
	v_add_u32_e32 v116, s11, v144
	v_mov_b64_e32 v[112:113], s[76:77]
	v_mad_i64_i32 v[240:241], s[20:21], v116, s38, v[112:113]
	v_lshl_add_u64 v[240:241], v[240:241], 0, v[114:115]
	global_store_dwordx4 v[240:241], v[120:123], off nt
	v_mul_f32_e32 v118, v157, v157
	v_rcp_f32_e32 v234, v118
	s_nop 0
	v_pk_mul_f32 v[106:107], v[110:111], v[106:107]
	v_pk_fma_f32 v[120:121], v[126:127], v[234:235], v[234:235] op_sel_hi:[1,0,0]
	v_pk_fma_f32 v[122:123], v[158:159], v[234:235], v[234:235] op_sel_hi:[1,0,0]
	v_rcp_f32_e32 v120, v120
	v_rcp_f32_e32 v122, v122
	v_rcp_f32_e32 v123, v123
	v_rcp_f32_e32 v121, v121
	v_pk_mul_f32 v[104:105], v[108:109], v[104:105]
	v_pk_mul_f32 v[96:97], v[100:101], v[96:97]
	v_pk_mul_f32 v[106:107], v[106:107], v[120:121]
	v_pk_mul_f32 v[104:105], v[104:105], v[122:123]
	v_pk_mul_f32 v[108:109], v[102:103], v[124:125] op_sel_hi:[1,0]
	v_pk_mul_f32 v[110:111], v[100:101], v[124:125] op_sel_hi:[1,0]
	v_exp_f32_e32 v108, v108
	v_exp_f32_e32 v110, v110
	v_exp_f32_e32 v109, v109
	v_exp_f32_e32 v111, v111
	v_cvt_pk_bf16_f32 v104, v104, v105
	v_cvt_pk_bf16_f32 v105, v106, v107
	v_pk_fma_f32 v[106:107], v[108:109], v[234:235], v[234:235] op_sel_hi:[1,0,0]
	v_pk_fma_f32 v[108:109], v[110:111], v[234:235], v[234:235] op_sel_hi:[1,0,0]
	v_rcp_f32_e32 v106, v106
	v_rcp_f32_e32 v108, v108
	v_rcp_f32_e32 v109, v109
	v_rcp_f32_e32 v107, v107
	v_pk_mul_f32 v[98:99], v[102:103], v[98:99]
	v_pk_mul_f32 v[88:89], v[92:93], v[88:89]
	v_pk_mul_f32 v[96:97], v[96:97], v[108:109]
	v_pk_mul_f32 v[102:103], v[106:107], 1.0 op_sel_hi:[1,0]
	v_cvt_pk_bf16_f32 v106, v96, v97
	ds_read2_b32 v[96:97], v154 offset0:32 offset1:48
	v_pk_mul_f32 v[98:99], v[98:99], v[102:103]
	v_pk_mul_f32 v[90:91], v[94:95], v[90:91]
	v_cvt_pk_bf16_f32 v107, v98, v99
	s_waitcnt lgkmcnt(0)
	v_mul_f32_e32 v100, 0xbfb8aa3b, v96
	v_pk_mul_f32 v[102:103], v[94:95], v[100:101] op_sel_hi:[1,0]
	v_pk_mul_f32 v[108:109], v[92:93], v[100:101] op_sel_hi:[1,0]
	v_exp_f32_e32 v102, v102
	v_exp_f32_e32 v108, v108
	v_exp_f32_e32 v103, v103
	v_exp_f32_e32 v109, v109
	s_mov_b32 s98, 0x16000
	v_lshl_add_u64 v[98:99], v[240:241], 0, s[98:99]
	global_store_dwordx4 v[98:99], v[104:107], off nt
	v_mul_f32_e32 v236, v96, v96
	v_rcp_f32_e32 v236, v236
	s_nop 0
	v_pk_fma_f32 v[98:99], v[102:103], v[236:237], v[236:237] op_sel_hi:[1,0,0]
	v_pk_fma_f32 v[102:103], v[108:109], v[236:237], v[236:237] op_sel_hi:[1,0,0]
	v_rcp_f32_e32 v98, v98
	v_rcp_f32_e32 v102, v102
	v_rcp_f32_e32 v103, v103
	v_rcp_f32_e32 v99, v99
	v_pk_mul_f32 v[82:83], v[86:87], v[82:83]
	v_pk_mul_f32 v[88:89], v[88:89], v[102:103]
	v_pk_mul_f32 v[92:93], v[86:87], v[100:101] op_sel_hi:[1,0]
	v_exp_f32_e32 v92, v92
	v_exp_f32_e32 v93, v93
	v_pk_mul_f32 v[90:91], v[90:91], v[98:99]
	v_pk_mul_f32 v[94:95], v[84:85], v[100:101] op_sel_hi:[1,0]
	v_cvt_pk_bf16_f32 v88, v88, v89
	v_exp_f32_e32 v94, v94
	v_exp_f32_e32 v95, v95
	v_cvt_pk_bf16_f32 v89, v90, v91
	v_pk_fma_f32 v[90:91], v[92:93], v[236:237], v[236:237] op_sel_hi:[1,0,0]
	v_pk_mul_f32 v[80:81], v[84:85], v[80:81]
	v_rcp_f32_e32 v90, v90
	v_rcp_f32_e32 v91, v91
	v_pk_fma_f32 v[92:93], v[94:95], v[236:237], v[236:237] op_sel_hi:[1,0,0]
	v_pk_mul_f32 v[74:75], v[78:79], v[74:75]
	v_rcp_f32_e32 v92, v92
	v_rcp_f32_e32 v93, v93
	v_pk_mul_f32 v[82:83], v[82:83], v[90:91]
	v_pk_mul_f32 v[72:73], v[76:77], v[72:73]
	v_cvt_pk_bf16_f32 v91, v82, v83
	v_mul_f32_e32 v82, 0xbfb8aa3b, v97
	v_pk_mul_f32 v[80:81], v[80:81], v[92:93]
	v_pk_mul_f32 v[84:85], v[78:79], v[82:83] op_sel_hi:[1,0]
	v_pk_mul_f32 v[86:87], v[76:77], v[82:83] op_sel_hi:[1,0]
	v_exp_f32_e32 v84, v84
	v_exp_f32_e32 v86, v86
	v_exp_f32_e32 v85, v85
	v_exp_f32_e32 v87, v87
	v_cvt_pk_bf16_f32 v90, v80, v81
	v_mul_f32_e32 v238, v97, v97
	v_rcp_f32_e32 v238, v238
	s_nop 0
	v_pk_fma_f32 v[84:85], v[84:85], v[238:239], v[238:239] op_sel_hi:[1,0,0]
	v_pk_fma_f32 v[86:87], v[86:87], v[238:239], v[238:239] op_sel_hi:[1,0,0]
	v_rcp_f32_e32 v84, v84
	v_rcp_f32_e32 v86, v86
	v_rcp_f32_e32 v87, v87
	v_rcp_f32_e32 v85, v85
	s_mov_b32 s98, 0x2c000
	v_lshl_add_u64 v[80:81], v[240:241], 0, s[98:99]
	global_store_dwordx4 v[80:81], v[88:91], off nt
	v_pk_mul_f32 v[74:75], v[74:75], v[84:85]
	v_pk_mul_f32 v[72:73], v[72:73], v[86:87]
	v_pk_mul_f32 v[76:77], v[70:71], v[82:83] op_sel_hi:[1,0]
	v_pk_mul_f32 v[78:79], v[68:69], v[82:83] op_sel_hi:[1,0]
	v_exp_f32_e32 v76, v76
	v_exp_f32_e32 v78, v78
	v_exp_f32_e32 v77, v77
	v_exp_f32_e32 v79, v79
	v_cvt_pk_bf16_f32 v72, v72, v73
	v_cvt_pk_bf16_f32 v73, v74, v75
	v_pk_fma_f32 v[74:75], v[76:77], v[238:239], v[238:239] op_sel_hi:[1,0,0]
	v_pk_fma_f32 v[76:77], v[78:79], v[238:239], v[238:239] op_sel_hi:[1,0,0]
	v_rcp_f32_e32 v74, v74
	v_rcp_f32_e32 v76, v76
	v_rcp_f32_e32 v77, v77
	v_rcp_f32_e32 v75, v75
	v_pk_mul_f32 v[64:65], v[68:69], v[64:65]
	v_pk_mul_f32 v[66:67], v[70:71], v[66:67]
	v_pk_mul_f32 v[64:65], v[64:65], v[76:77]
	v_pk_mul_f32 v[70:71], v[74:75], 1.0 op_sel_hi:[1,0]
	v_cvt_pk_bf16_f32 v74, v64, v65
	ds_read2_b32 v[64:65], v154 offset0:128 offset1:144
	v_pk_mul_f32 v[66:67], v[66:67], v[70:71]
	v_pk_mul_f32 v[56:57], v[60:61], v[56:57]
	v_cvt_pk_bf16_f32 v75, v66, v67
	s_waitcnt lgkmcnt(0)
	v_mul_f32_e32 v68, 0xbfb8aa3b, v64
	v_pk_mul_f32 v[70:71], v[62:63], v[68:69] op_sel_hi:[1,0]
	v_pk_mul_f32 v[76:77], v[60:61], v[68:69] op_sel_hi:[1,0]
	v_exp_f32_e32 v70, v70
	v_exp_f32_e32 v76, v76
	v_exp_f32_e32 v71, v71
	v_exp_f32_e32 v77, v77
	s_mov_b32 s98, 0x42000
	v_lshl_add_u64 v[66:67], v[240:241], 0, s[98:99]
	global_store_dwordx4 v[66:67], v[72:75], off nt
	v_mul_f32_e32 v232, v64, v64
	v_rcp_f32_e32 v232, v232
	s_nop 0
	v_pk_fma_f32 v[66:67], v[70:71], v[232:233], v[232:233] op_sel_hi:[1,0,0]
	v_pk_fma_f32 v[70:71], v[76:77], v[232:233], v[232:233] op_sel_hi:[1,0,0]
	v_rcp_f32_e32 v66, v66
	v_rcp_f32_e32 v70, v70
	v_rcp_f32_e32 v71, v71
	v_rcp_f32_e32 v67, v67
	v_pk_mul_f32 v[58:59], v[62:63], v[58:59]
	v_pk_mul_f32 v[56:57], v[56:57], v[70:71]
	v_pk_mul_f32 v[60:61], v[54:55], v[68:69] op_sel_hi:[1,0]
	v_exp_f32_e32 v60, v60
	v_exp_f32_e32 v61, v61
	v_pk_mul_f32 v[58:59], v[58:59], v[66:67]
	v_pk_mul_f32 v[62:63], v[52:53], v[68:69] op_sel_hi:[1,0]
	v_cvt_pk_bf16_f32 v56, v56, v57
	v_exp_f32_e32 v62, v62
	v_exp_f32_e32 v63, v63
	v_cvt_pk_bf16_f32 v57, v58, v59
	v_pk_fma_f32 v[58:59], v[60:61], v[232:233], v[232:233] op_sel_hi:[1,0,0]
	v_pk_mul_f32 v[50:51], v[54:55], v[50:51]
	v_rcp_f32_e32 v58, v58
	v_rcp_f32_e32 v59, v59
	v_pk_fma_f32 v[60:61], v[62:63], v[232:233], v[232:233] op_sel_hi:[1,0,0]
	v_pk_mul_f32 v[48:49], v[52:53], v[48:49]
	v_rcp_f32_e32 v60, v60
	v_rcp_f32_e32 v61, v61
	v_pk_mul_f32 v[50:51], v[50:51], v[58:59]
	v_pk_mul_f32 v[42:43], v[46:47], v[42:43]
	v_cvt_pk_bf16_f32 v59, v50, v51
	v_mul_f32_e32 v50, 0xbfb8aa3b, v65
	v_pk_mul_f32 v[48:49], v[48:49], v[60:61]
	v_pk_mul_f32 v[52:53], v[46:47], v[50:51] op_sel_hi:[1,0]
	v_pk_mul_f32 v[54:55], v[44:45], v[50:51] op_sel_hi:[1,0]
	v_exp_f32_e32 v52, v52
	v_exp_f32_e32 v54, v54
	v_exp_f32_e32 v53, v53
	v_exp_f32_e32 v55, v55
	v_cvt_pk_bf16_f32 v58, v48, v49
	v_mul_f32_e32 v234, v65, v65
	v_rcp_f32_e32 v234, v234
	s_nop 0
	v_pk_fma_f32 v[52:53], v[52:53], v[234:235], v[234:235] op_sel_hi:[1,0,0]
	v_pk_fma_f32 v[54:55], v[54:55], v[234:235], v[234:235] op_sel_hi:[1,0,0]
	v_rcp_f32_e32 v52, v52
	v_rcp_f32_e32 v54, v54
	v_rcp_f32_e32 v55, v55
	v_rcp_f32_e32 v53, v53
	s_mov_b32 s98, 0xb0000
	v_lshl_add_u64 v[48:49], v[240:241], 0, s[98:99]
	global_store_dwordx4 v[48:49], v[56:59], off nt
	v_pk_mul_f32 v[40:41], v[44:45], v[40:41]
	v_pk_mul_f32 v[42:43], v[42:43], v[52:53]
	v_pk_mul_f32 v[40:41], v[40:41], v[54:55]
	v_pk_mul_f32 v[44:45], v[38:39], v[50:51] op_sel_hi:[1,0]
	v_pk_mul_f32 v[46:47], v[36:37], v[50:51] op_sel_hi:[1,0]
	v_exp_f32_e32 v44, v44
	v_exp_f32_e32 v46, v46
	v_exp_f32_e32 v45, v45
	v_exp_f32_e32 v47, v47
	v_cvt_pk_bf16_f32 v40, v40, v41
	v_cvt_pk_bf16_f32 v41, v42, v43
	v_pk_fma_f32 v[42:43], v[44:45], v[234:235], v[234:235] op_sel_hi:[1,0,0]
	v_pk_fma_f32 v[44:45], v[46:47], v[234:235], v[234:235] op_sel_hi:[1,0,0]
	v_rcp_f32_e32 v42, v42
	v_rcp_f32_e32 v44, v44
	v_rcp_f32_e32 v45, v45
	v_rcp_f32_e32 v43, v43
	v_pk_mul_f32 v[32:33], v[36:37], v[32:33]
	v_pk_mul_f32 v[34:35], v[38:39], v[34:35]
	v_pk_mul_f32 v[32:33], v[32:33], v[44:45]
	v_pk_mul_f32 v[38:39], v[42:43], 1.0 op_sel_hi:[1,0]
	v_cvt_pk_bf16_f32 v42, v32, v33
	ds_read2_b32 v[32:33], v154 offset0:160 offset1:176
	v_pk_mul_f32 v[34:35], v[34:35], v[38:39]
	v_pk_mul_f32 v[24:25], v[28:29], v[24:25]
	v_cvt_pk_bf16_f32 v43, v34, v35
	s_waitcnt lgkmcnt(0)
	v_mul_f32_e32 v36, 0xbfb8aa3b, v32
	v_pk_mul_f32 v[38:39], v[30:31], v[36:37] op_sel_hi:[1,0]
	v_pk_mul_f32 v[44:45], v[28:29], v[36:37] op_sel_hi:[1,0]
	v_exp_f32_e32 v38, v38
	v_exp_f32_e32 v44, v44
	v_exp_f32_e32 v39, v39
	v_exp_f32_e32 v45, v45
	s_mov_b32 s98, 0xc6000
	v_lshl_add_u64 v[34:35], v[240:241], 0, s[98:99]
	global_store_dwordx4 v[34:35], v[40:43], off nt
	v_mul_f32_e32 v236, v32, v32
	v_rcp_f32_e32 v236, v236
	s_nop 0
	v_pk_fma_f32 v[34:35], v[38:39], v[236:237], v[236:237] op_sel_hi:[1,0,0]
	v_pk_fma_f32 v[38:39], v[44:45], v[236:237], v[236:237] op_sel_hi:[1,0,0]
	v_rcp_f32_e32 v34, v34
	v_rcp_f32_e32 v38, v38
	v_rcp_f32_e32 v39, v39
	v_rcp_f32_e32 v35, v35
	v_pk_mul_f32 v[26:27], v[30:31], v[26:27]
	v_pk_mul_f32 v[24:25], v[24:25], v[38:39]
	v_pk_mul_f32 v[28:29], v[22:23], v[36:37] op_sel_hi:[1,0]
	v_exp_f32_e32 v28, v28
	v_exp_f32_e32 v29, v29
	v_pk_mul_f32 v[26:27], v[26:27], v[34:35]
	v_pk_mul_f32 v[30:31], v[20:21], v[36:37] op_sel_hi:[1,0]
	v_cvt_pk_bf16_f32 v24, v24, v25
	v_exp_f32_e32 v30, v30
	v_exp_f32_e32 v31, v31
	v_cvt_pk_bf16_f32 v25, v26, v27
	v_pk_fma_f32 v[26:27], v[28:29], v[236:237], v[236:237] op_sel_hi:[1,0,0]
	v_pk_mul_f32 v[18:19], v[22:23], v[18:19]
	v_rcp_f32_e32 v26, v26
	v_rcp_f32_e32 v27, v27
	v_pk_fma_f32 v[28:29], v[30:31], v[236:237], v[236:237] op_sel_hi:[1,0,0]
	v_pk_mul_f32 v[16:17], v[20:21], v[16:17]
	v_rcp_f32_e32 v28, v28
	v_rcp_f32_e32 v29, v29
	v_pk_mul_f32 v[18:19], v[18:19], v[26:27]
	v_pk_mul_f32 v[10:11], v[14:15], v[10:11]
	v_cvt_pk_bf16_f32 v27, v18, v19
	v_mul_f32_e32 v18, 0xbfb8aa3b, v33
	v_pk_mul_f32 v[16:17], v[16:17], v[28:29]
	v_pk_mul_f32 v[20:21], v[14:15], v[18:19] op_sel_hi:[1,0]
	v_pk_mul_f32 v[22:23], v[12:13], v[18:19] op_sel_hi:[1,0]
	v_exp_f32_e32 v20, v20
	v_exp_f32_e32 v22, v22
	v_exp_f32_e32 v21, v21
	v_exp_f32_e32 v23, v23
	v_cvt_pk_bf16_f32 v26, v16, v17
	v_mul_f32_e32 v238, v33, v33
	v_rcp_f32_e32 v238, v238
	s_nop 0
	v_pk_fma_f32 v[20:21], v[20:21], v[238:239], v[238:239] op_sel_hi:[1,0,0]
	v_pk_fma_f32 v[22:23], v[22:23], v[238:239], v[238:239] op_sel_hi:[1,0,0]
	v_rcp_f32_e32 v20, v20
	v_rcp_f32_e32 v22, v22
	v_rcp_f32_e32 v23, v23
	v_rcp_f32_e32 v21, v21
	s_mov_b32 s98, 0xdc000
	v_lshl_add_u64 v[16:17], v[240:241], 0, s[98:99]
	global_store_dwordx4 v[16:17], v[24:27], off nt
	v_pk_mul_f32 v[8:9], v[12:13], v[8:9]
	v_pk_mul_f32 v[10:11], v[10:11], v[20:21]
	v_pk_mul_f32 v[8:9], v[8:9], v[22:23]
	v_pk_mul_f32 v[12:13], v[6:7], v[18:19] op_sel_hi:[1,0]
	v_pk_mul_f32 v[14:15], v[4:5], v[18:19] op_sel_hi:[1,0]
	v_exp_f32_e32 v12, v12
	v_exp_f32_e32 v14, v14
	v_exp_f32_e32 v13, v13
	v_exp_f32_e32 v15, v15
	v_cvt_pk_bf16_f32 v8, v8, v9
	v_cvt_pk_bf16_f32 v9, v10, v11
	v_pk_fma_f32 v[10:11], v[12:13], v[238:239], v[238:239] op_sel_hi:[1,0,0]
	v_pk_fma_f32 v[12:13], v[14:15], v[238:239], v[238:239] op_sel_hi:[1,0,0]
	v_rcp_f32_e32 v10, v10
	v_rcp_f32_e32 v12, v12
	v_rcp_f32_e32 v13, v13
	v_rcp_f32_e32 v11, v11
	v_pk_mul_f32 v[0:1], v[4:5], v[0:1]
	v_pk_mul_f32 v[2:3], v[6:7], v[2:3]
	v_pk_mul_f32 v[0:1], v[0:1], v[12:13]
	v_pk_mul_f32 v[6:7], v[10:11], 1.0 op_sel_hi:[1,0]
	v_cvt_pk_bf16_f32 v10, v0, v1
	v_pk_mul_f32 v[2:3], v[2:3], v[6:7]
	v_cvt_pk_bf16_f32 v11, v2, v3
	s_mov_b32 s98, 0xf2000
	v_lshl_add_u64 v[0:1], v[240:241], 0, s[98:99]
	s_andn2_b64 vcc, exec, s[0:1]
	s_mov_b64 s[0:1], -1
	global_store_dwordx4 v[0:1], v[8:11], off nt
	s_cbranch_vccnz .LBB0_701
	s_andn2_b64 vcc, exec, s[4:5]
	s_cbranch_vccnz .LBB0_700
	s_barrier
	s_branch .LBB0_700
